# GEMM K-loops: first iteration peeled so the first MFMA of every accumulator takes C=0; the 128 accumulator-zeroing moves per tile header removed
# speedup vs baseline: 1.0076x; 1.0076x over previous
.LBB0_565:
	s_ashr_i32 s25, s24, 31
	s_lshl_b64 s[26:27], s[24:25], 19
	s_add_u32 s26, s84, s26
	s_addc_u32 s27, s85, s27
	s_and_b64 s[28:29], s[10:11], exec
	s_cselect_b32 s3, s27, s1
	s_cselect_b32 s25, s26, s0
	s_ashr_i32 s23, s22, 31
	s_lshl_b64 s[28:29], s[22:23], 19
	s_add_u32 s28, s37, s28
	s_addc_u32 s29, s38, s29
	s_and_b64 s[34:35], s[10:11], exec
	s_cselect_b32 s23, s29, s31
	s_cselect_b32 s48, s28, s30
	s_add_u32 s0, s0, 0x40080
	s_addc_u32 s1, s1, 0
	s_add_u32 s49, s30, 0x100
	s_addc_u32 s50, s31, 0
	s_mov_b32 s51, -2
	s_waitcnt lgkmcnt(0)
	s_add_u32 s30, s0, 0xfffc0080
	s_addc_u32 s31, s1, -1
	s_add_i32 s52, 0, 0x10000
	s_cmp_eq_u32 s51, 12
	s_cselect_b32 s35, s3, s31
	s_cselect_b32 s34, s25, s30
	s_cselect_b32 s31, s23, s50
	s_cselect_b32 s30, s48, s49
	s_add_i32 s54, 0, 0x14000
	v_add_u32_e32 v158, s52, v199
	v_add_u32_e32 v174, s54, v199
	ds_read_b128 v[134:137], v158
	ds_read_b128 v[150:153], v158 offset:1024
	ds_read_b128 v[154:157], v158 offset:2048
	ds_read_b128 v[158:161], v158 offset:3072
	ds_read_b128 v[162:165], v174
	ds_read_b128 v[166:169], v174 offset:1024
	ds_read_b128 v[170:173], v174 offset:2048
	ds_read_b128 v[182:185], v174 offset:3072
	v_lshl_add_u64 v[174:175], s[0:1], 0, v[146:147]
	s_add_i32 m0, s39, 0xc000
	ds_read_b128 v[186:189], v201
	ds_read_b128 v[202:205], v201 offset:1024
	ds_read_b128 v[206:209], v201 offset:2048
	ds_read_b128 v[210:213], v201 offset:3072
	ds_read_b128 v[214:217], v201 offset:4096
	ds_read_b128 v[218:221], v201 offset:5120
	ds_read_b128 v[222:225], v201 offset:6144
	ds_read_b128 v[226:229], v201 offset:7168
	global_load_lds_dwordx4 v[174:175], off
	v_lshl_add_u64 v[174:175], s[0:1], 0, v[148:149]
	s_add_i32 m0, s39, 0xe000
	s_nop 0
	global_load_lds_dwordx4 v[174:175], off
	s_waitcnt vmcnt(8)
	s_waitcnt lgkmcnt(0)
	s_barrier
	s_setprio 1
	s_waitcnt lgkmcnt(0)
	v_mfma_f32_16x16x32_bf16 v[130:133], v[134:137], v[186:189], 0
	v_mfma_f32_16x16x32_bf16 v[130:133], v[150:153], v[202:205], v[130:133]
	v_mfma_f32_16x16x32_bf16 v[126:129], v[154:157], v[186:189], 0
	v_mfma_f32_16x16x32_bf16 v[126:129], v[158:161], v[202:205], v[126:129]
	v_mfma_f32_16x16x32_bf16 v[114:117], v[134:137], v[206:209], 0
	v_mfma_f32_16x16x32_bf16 v[114:117], v[150:153], v[210:213], v[114:117]
	v_mfma_f32_16x16x32_bf16 v[110:113], v[154:157], v[206:209], 0
	v_mfma_f32_16x16x32_bf16 v[110:113], v[158:161], v[210:213], v[110:113]
	v_mfma_f32_16x16x32_bf16 v[98:101], v[134:137], v[214:217], 0
	v_mfma_f32_16x16x32_bf16 v[98:101], v[150:153], v[218:221], v[98:101]
	v_mfma_f32_16x16x32_bf16 v[94:97], v[154:157], v[214:217], 0
	v_mfma_f32_16x16x32_bf16 v[94:97], v[158:161], v[218:221], v[94:97]
	v_mfma_f32_16x16x32_bf16 v[82:85], v[134:137], v[222:225], 0
	v_mfma_f32_16x16x32_bf16 v[82:85], v[150:153], v[226:229], v[82:85]
	v_mfma_f32_16x16x32_bf16 v[78:81], v[154:157], v[222:225], 0
	v_mfma_f32_16x16x32_bf16 v[78:81], v[158:161], v[226:229], v[78:81]
	s_setprio 0
	s_setprio 1
	v_mfma_f32_16x16x32_bf16 v[122:125], v[162:165], v[186:189], 0
	v_mfma_f32_16x16x32_bf16 v[122:125], v[166:169], v[202:205], v[122:125]
	v_mfma_f32_16x16x32_bf16 v[118:121], v[170:173], v[186:189], 0
	v_mfma_f32_16x16x32_bf16 v[118:121], v[182:185], v[202:205], v[118:121]
	v_mfma_f32_16x16x32_bf16 v[106:109], v[162:165], v[206:209], 0
	v_mfma_f32_16x16x32_bf16 v[106:109], v[166:169], v[210:213], v[106:109]
	v_mfma_f32_16x16x32_bf16 v[102:105], v[170:173], v[206:209], 0
	v_mfma_f32_16x16x32_bf16 v[102:105], v[182:185], v[210:213], v[102:105]
	v_mfma_f32_16x16x32_bf16 v[90:93], v[162:165], v[214:217], 0
	v_mfma_f32_16x16x32_bf16 v[90:93], v[166:169], v[218:221], v[90:93]
	v_mfma_f32_16x16x32_bf16 v[86:89], v[170:173], v[214:217], 0
	v_mfma_f32_16x16x32_bf16 v[86:89], v[182:185], v[218:221], v[86:89]
	v_mfma_f32_16x16x32_bf16 v[74:77], v[162:165], v[222:225], 0
	v_mfma_f32_16x16x32_bf16 v[74:77], v[166:169], v[226:229], v[74:77]
	v_mfma_f32_16x16x32_bf16 v[70:73], v[170:173], v[222:225], 0
	v_mfma_f32_16x16x32_bf16 v[70:73], v[182:185], v[226:229], v[70:73]
	s_setprio 0
	s_barrier
	s_add_i32 s52, s52, s36
	v_lshl_add_u64 v[174:175], s[30:31], 0, v[0:1]
	s_mov_b32 m0, s52
	ds_read_b128 v[186:189], v201 offset:16384
	ds_read_b128 v[202:205], v201 offset:17408
	ds_read_b128 v[206:209], v201 offset:18432
	ds_read_b128 v[210:213], v201 offset:19456
	ds_read_b128 v[214:217], v201 offset:20480
	ds_read_b128 v[218:221], v201 offset:21504
	ds_read_b128 v[222:225], v201 offset:22528
	ds_read_b128 v[226:229], v201 offset:23552
	global_load_lds_dwordx4 v[174:175], off
	s_add_i32 m0, s52, 0x2000
	s_add_u32 s52, s30, 0x40000
	v_lshl_add_u64 v[190:191], s[30:31], 0, v[14:15]
	s_addc_u32 s53, s31, 0
	s_add_i32 s54, s54, s36
	global_load_lds_dwordx4 v[190:191], off
	v_lshl_add_u64 v[230:231], s[52:53], 0, v[0:1]
	s_mov_b32 m0, s54
	v_lshl_add_u64 v[232:233], s[34:35], 0, v[138:139]
	global_load_lds_dwordx4 v[230:231], off
	v_lshl_add_u64 v[230:231], s[52:53], 0, v[14:15]
	s_add_i32 m0, s54, 0x2000
	s_nop 0
	global_load_lds_dwordx4 v[230:231], off
	v_lshl_add_u64 v[230:231], s[34:35], 0, v[140:141]
	s_mov_b32 m0, s39
	s_nop 0
	global_load_lds_dwordx4 v[230:231], off
	s_mov_b32 m0, s40
	s_nop 0
	global_load_lds_dwordx4 v[232:233], off
	s_waitcnt vmcnt(8)
	s_waitcnt lgkmcnt(0)
	s_barrier
	s_setprio 1
	s_waitcnt lgkmcnt(0)
	v_mfma_f32_16x16x32_bf16 v[66:69], v[134:137], v[186:189], 0
	v_mfma_f32_16x16x32_bf16 v[66:69], v[150:153], v[202:205], v[66:69]
	v_mfma_f32_16x16x32_bf16 v[62:65], v[154:157], v[186:189], 0
	v_mfma_f32_16x16x32_bf16 v[62:65], v[158:161], v[202:205], v[62:65]
	v_mfma_f32_16x16x32_bf16 v[50:53], v[134:137], v[206:209], 0
	v_mfma_f32_16x16x32_bf16 v[50:53], v[150:153], v[210:213], v[50:53]
	v_mfma_f32_16x16x32_bf16 v[46:49], v[154:157], v[206:209], 0
	v_mfma_f32_16x16x32_bf16 v[46:49], v[158:161], v[210:213], v[46:49]
	v_mfma_f32_16x16x32_bf16 v[34:37], v[134:137], v[214:217], 0
	v_mfma_f32_16x16x32_bf16 v[34:37], v[150:153], v[218:221], v[34:37]
	v_mfma_f32_16x16x32_bf16 v[30:33], v[154:157], v[214:217], 0
	v_mfma_f32_16x16x32_bf16 v[30:33], v[158:161], v[218:221], v[30:33]
	v_mfma_f32_16x16x32_bf16 v[18:21], v[134:137], v[222:225], 0
	v_mfma_f32_16x16x32_bf16 v[18:21], v[150:153], v[226:229], v[18:21]
	v_mfma_f32_16x16x32_bf16 v[10:13], v[154:157], v[222:225], 0
	v_mfma_f32_16x16x32_bf16 v[10:13], v[158:161], v[226:229], v[10:13]
	s_setprio 0
	s_setprio 1
	v_mfma_f32_16x16x32_bf16 v[58:61], v[162:165], v[186:189], 0
	v_mfma_f32_16x16x32_bf16 v[58:61], v[166:169], v[202:205], v[58:61]
	v_mfma_f32_16x16x32_bf16 v[54:57], v[170:173], v[186:189], 0
	v_mfma_f32_16x16x32_bf16 v[54:57], v[182:185], v[202:205], v[54:57]
	v_mfma_f32_16x16x32_bf16 v[42:45], v[162:165], v[206:209], 0
	v_mfma_f32_16x16x32_bf16 v[42:45], v[166:169], v[210:213], v[42:45]
	v_mfma_f32_16x16x32_bf16 v[38:41], v[170:173], v[206:209], 0
	v_mfma_f32_16x16x32_bf16 v[38:41], v[182:185], v[210:213], v[38:41]
	v_mfma_f32_16x16x32_bf16 v[26:29], v[162:165], v[214:217], 0
	v_mfma_f32_16x16x32_bf16 v[26:29], v[166:169], v[218:221], v[26:29]
	v_mfma_f32_16x16x32_bf16 v[22:25], v[170:173], v[214:217], 0
	v_mfma_f32_16x16x32_bf16 v[22:25], v[182:185], v[218:221], v[22:25]
	v_mfma_f32_16x16x32_bf16 v[6:9], v[162:165], v[222:225], 0
	v_mfma_f32_16x16x32_bf16 v[6:9], v[166:169], v[226:229], v[6:9]
	v_mfma_f32_16x16x32_bf16 v[2:5], v[170:173], v[222:225], 0
	v_mfma_f32_16x16x32_bf16 v[2:5], v[182:185], v[226:229], v[2:5]
	s_setprio 0
	s_barrier
	s_add_i32 s52, 0, 0x18000
	s_add_i32 s53, 0, 0x1c000
	v_add_u32_e32 v158, s52, v199
	v_add_u32_e32 v182, s53, v199
	ds_read_b128 v[134:137], v158
	ds_read_b128 v[150:153], v158 offset:1024
	ds_read_b128 v[154:157], v158 offset:2048
	ds_read_b128 v[158:161], v158 offset:3072
	ds_read_b128 v[162:165], v182
	ds_read_b128 v[166:169], v182 offset:1024
	ds_read_b128 v[170:173], v182 offset:2048
	ds_read_b128 v[182:185], v182 offset:3072
	s_add_u32 s34, s34, 0x40000
	s_addc_u32 s35, s35, 0
	s_mov_b32 m0, s41
	v_lshl_add_u64 v[234:235], s[34:35], 0, v[140:141]
	ds_read_b128 v[186:189], v201 offset:32768
	ds_read_b128 v[202:205], v201 offset:33792
	ds_read_b128 v[206:209], v201 offset:34816
	ds_read_b128 v[210:213], v201 offset:35840
	ds_read_b128 v[214:217], v201 offset:36864
	ds_read_b128 v[218:221], v201 offset:37888
	ds_read_b128 v[222:225], v201 offset:38912
	ds_read_b128 v[226:229], v201 offset:39936
	global_load_lds_dwordx4 v[234:235], off
	v_lshl_add_u64 v[234:235], s[34:35], 0, v[138:139]
	s_mov_b32 m0, s42
	s_nop 0
	global_load_lds_dwordx4 v[234:235], off
	s_waitcnt vmcnt(8)
	s_waitcnt lgkmcnt(0)
	s_barrier
	s_setprio 1
	s_waitcnt lgkmcnt(0)
	v_mfma_f32_16x16x32_bf16 v[130:133], v[134:137], v[186:189], v[130:133]
	v_mfma_f32_16x16x32_bf16 v[130:133], v[150:153], v[202:205], v[130:133]
	v_mfma_f32_16x16x32_bf16 v[126:129], v[154:157], v[186:189], v[126:129]
	v_mfma_f32_16x16x32_bf16 v[126:129], v[158:161], v[202:205], v[126:129]
	v_mfma_f32_16x16x32_bf16 v[114:117], v[134:137], v[206:209], v[114:117]
	v_mfma_f32_16x16x32_bf16 v[114:117], v[150:153], v[210:213], v[114:117]
	v_mfma_f32_16x16x32_bf16 v[110:113], v[154:157], v[206:209], v[110:113]
	v_mfma_f32_16x16x32_bf16 v[110:113], v[158:161], v[210:213], v[110:113]
	v_mfma_f32_16x16x32_bf16 v[98:101], v[134:137], v[214:217], v[98:101]
	v_mfma_f32_16x16x32_bf16 v[98:101], v[150:153], v[218:221], v[98:101]
	v_mfma_f32_16x16x32_bf16 v[94:97], v[154:157], v[214:217], v[94:97]
	v_mfma_f32_16x16x32_bf16 v[94:97], v[158:161], v[218:221], v[94:97]
	v_mfma_f32_16x16x32_bf16 v[82:85], v[134:137], v[222:225], v[82:85]
	v_mfma_f32_16x16x32_bf16 v[82:85], v[150:153], v[226:229], v[82:85]
	v_mfma_f32_16x16x32_bf16 v[78:81], v[154:157], v[222:225], v[78:81]
	v_mfma_f32_16x16x32_bf16 v[78:81], v[158:161], v[226:229], v[78:81]
	s_setprio 0
	s_setprio 1
	v_mfma_f32_16x16x32_bf16 v[122:125], v[162:165], v[186:189], v[122:125]
	v_mfma_f32_16x16x32_bf16 v[122:125], v[166:169], v[202:205], v[122:125]
	v_mfma_f32_16x16x32_bf16 v[118:121], v[170:173], v[186:189], v[118:121]
	v_mfma_f32_16x16x32_bf16 v[118:121], v[182:185], v[202:205], v[118:121]
	v_mfma_f32_16x16x32_bf16 v[106:109], v[162:165], v[206:209], v[106:109]
	v_mfma_f32_16x16x32_bf16 v[106:109], v[166:169], v[210:213], v[106:109]
	v_mfma_f32_16x16x32_bf16 v[102:105], v[170:173], v[206:209], v[102:105]
	v_mfma_f32_16x16x32_bf16 v[102:105], v[182:185], v[210:213], v[102:105]
	v_mfma_f32_16x16x32_bf16 v[90:93], v[162:165], v[214:217], v[90:93]
	v_mfma_f32_16x16x32_bf16 v[90:93], v[166:169], v[218:221], v[90:93]
	v_mfma_f32_16x16x32_bf16 v[86:89], v[170:173], v[214:217], v[86:89]
	v_mfma_f32_16x16x32_bf16 v[86:89], v[182:185], v[218:221], v[86:89]
	v_mfma_f32_16x16x32_bf16 v[74:77], v[162:165], v[222:225], v[74:77]
	v_mfma_f32_16x16x32_bf16 v[74:77], v[166:169], v[226:229], v[74:77]
	v_mfma_f32_16x16x32_bf16 v[70:73], v[170:173], v[222:225], v[70:73]
	v_mfma_f32_16x16x32_bf16 v[70:73], v[182:185], v[226:229], v[70:73]
	s_setprio 0
	s_barrier
	s_add_i32 s34, s52, s36
	v_lshl_add_u64 v[174:175], v[174:175], 0, s[92:93]
	s_mov_b32 m0, s34
	ds_read_b128 v[186:189], v201 offset:49152
	ds_read_b128 v[202:205], v201 offset:50176
	ds_read_b128 v[206:209], v201 offset:51200
	ds_read_b128 v[210:213], v201 offset:52224
	ds_read_b128 v[214:217], v201 offset:53248
	ds_read_b128 v[218:221], v201 offset:54272
	ds_read_b128 v[222:225], v201 offset:55296
	ds_read_b128 v[226:229], v201 offset:56320
	global_load_lds_dwordx4 v[174:175], off
	s_add_i32 m0, s34, 0x2000
	s_add_u32 s30, s30, 0x40080
	v_lshl_add_u64 v[174:175], v[190:191], 0, s[92:93]
	s_addc_u32 s31, s31, 0
	s_add_i32 s34, s53, s36
	global_load_lds_dwordx4 v[174:175], off
	v_lshl_add_u64 v[174:175], s[30:31], 0, v[0:1]
	s_mov_b32 m0, s34
	s_nop 0
	global_load_lds_dwordx4 v[174:175], off
	v_lshl_add_u64 v[174:175], s[30:31], 0, v[14:15]
	s_add_i32 m0, s34, 0x2000
	s_nop 0
	global_load_lds_dwordx4 v[174:175], off
	v_lshl_add_u64 v[174:175], v[230:231], 0, s[92:93]
	s_mov_b32 m0, s43
	s_nop 0
	global_load_lds_dwordx4 v[174:175], off
	v_lshl_add_u64 v[174:175], v[232:233], 0, s[92:93]
	s_mov_b32 m0, s44
	s_nop 0
	global_load_lds_dwordx4 v[174:175], off
	s_waitcnt vmcnt(8)
	s_waitcnt lgkmcnt(0)
	s_barrier
	s_setprio 1
	s_waitcnt lgkmcnt(0)
	v_mfma_f32_16x16x32_bf16 v[66:69], v[134:137], v[186:189], v[66:69]
	v_mfma_f32_16x16x32_bf16 v[66:69], v[150:153], v[202:205], v[66:69]
	v_mfma_f32_16x16x32_bf16 v[62:65], v[154:157], v[186:189], v[62:65]
	v_mfma_f32_16x16x32_bf16 v[62:65], v[158:161], v[202:205], v[62:65]
	v_mfma_f32_16x16x32_bf16 v[50:53], v[134:137], v[206:209], v[50:53]
	v_mfma_f32_16x16x32_bf16 v[50:53], v[150:153], v[210:213], v[50:53]
	v_mfma_f32_16x16x32_bf16 v[46:49], v[154:157], v[206:209], v[46:49]
	v_mfma_f32_16x16x32_bf16 v[46:49], v[158:161], v[210:213], v[46:49]
	v_mfma_f32_16x16x32_bf16 v[34:37], v[134:137], v[214:217], v[34:37]
	v_mfma_f32_16x16x32_bf16 v[34:37], v[150:153], v[218:221], v[34:37]
	v_mfma_f32_16x16x32_bf16 v[30:33], v[154:157], v[214:217], v[30:33]
	v_mfma_f32_16x16x32_bf16 v[30:33], v[158:161], v[218:221], v[30:33]
	v_mfma_f32_16x16x32_bf16 v[18:21], v[134:137], v[222:225], v[18:21]
	v_mfma_f32_16x16x32_bf16 v[18:21], v[150:153], v[226:229], v[18:21]
	v_mfma_f32_16x16x32_bf16 v[10:13], v[154:157], v[222:225], v[10:13]
	v_mfma_f32_16x16x32_bf16 v[10:13], v[158:161], v[226:229], v[10:13]
	s_setprio 0
	s_setprio 1
	v_mfma_f32_16x16x32_bf16 v[58:61], v[162:165], v[186:189], v[58:61]
	v_mfma_f32_16x16x32_bf16 v[58:61], v[166:169], v[202:205], v[58:61]
	v_mfma_f32_16x16x32_bf16 v[54:57], v[170:173], v[186:189], v[54:57]
	v_mfma_f32_16x16x32_bf16 v[54:57], v[182:185], v[202:205], v[54:57]
	v_mfma_f32_16x16x32_bf16 v[42:45], v[162:165], v[206:209], v[42:45]
	v_mfma_f32_16x16x32_bf16 v[42:45], v[166:169], v[210:213], v[42:45]
	v_mfma_f32_16x16x32_bf16 v[38:41], v[170:173], v[206:209], v[38:41]
	v_mfma_f32_16x16x32_bf16 v[38:41], v[182:185], v[210:213], v[38:41]
	v_mfma_f32_16x16x32_bf16 v[26:29], v[162:165], v[214:217], v[26:29]
	v_mfma_f32_16x16x32_bf16 v[26:29], v[166:169], v[218:221], v[26:29]
	v_mfma_f32_16x16x32_bf16 v[22:25], v[170:173], v[214:217], v[22:25]
	v_mfma_f32_16x16x32_bf16 v[22:25], v[182:185], v[218:221], v[22:25]
	v_mfma_f32_16x16x32_bf16 v[6:9], v[162:165], v[222:225], v[6:9]
	v_mfma_f32_16x16x32_bf16 v[6:9], v[166:169], v[226:229], v[6:9]
	v_mfma_f32_16x16x32_bf16 v[2:5], v[170:173], v[222:225], v[2:5]
	v_mfma_f32_16x16x32_bf16 v[2:5], v[182:185], v[226:229], v[2:5]
	s_setprio 0
	s_barrier
	s_add_i32 s51, s51, 2
	s_add_u32 s0, s0, 0x100
	s_addc_u32 s1, s1, 0
	s_add_u32 s49, s49, 0x100
	s_addc_u32 s50, s50, 0
	s_cmp_gt_u32 s51, 13
	s_cbranch_scc1 .Lpeel_exit_1
.LBB0_566:
	s_add_u32 s30, s0, 0xfffc0080
	s_addc_u32 s31, s1, -1
	s_add_i32 s52, 0, 0x10000
	s_cmp_eq_u32 s51, 12
	s_cselect_b32 s35, s3, s31
	s_cselect_b32 s34, s25, s30
	s_cselect_b32 s31, s23, s50
	s_cselect_b32 s30, s48, s49
	s_add_i32 s54, 0, 0x14000
	v_add_u32_e32 v158, s52, v199
	v_add_u32_e32 v174, s54, v199
	ds_read_b128 v[134:137], v158
	ds_read_b128 v[150:153], v158 offset:1024
	ds_read_b128 v[154:157], v158 offset:2048
	ds_read_b128 v[158:161], v158 offset:3072
	ds_read_b128 v[162:165], v174
	ds_read_b128 v[166:169], v174 offset:1024
	ds_read_b128 v[170:173], v174 offset:2048
	ds_read_b128 v[182:185], v174 offset:3072
	v_lshl_add_u64 v[174:175], s[0:1], 0, v[146:147]
	s_add_i32 m0, s39, 0xc000
	ds_read_b128 v[186:189], v201
	ds_read_b128 v[202:205], v201 offset:1024
	ds_read_b128 v[206:209], v201 offset:2048
	ds_read_b128 v[210:213], v201 offset:3072
	ds_read_b128 v[214:217], v201 offset:4096
	ds_read_b128 v[218:221], v201 offset:5120
	ds_read_b128 v[222:225], v201 offset:6144
	ds_read_b128 v[226:229], v201 offset:7168
	global_load_lds_dwordx4 v[174:175], off
	v_lshl_add_u64 v[174:175], s[0:1], 0, v[148:149]
	s_add_i32 m0, s39, 0xe000
	s_nop 0
	global_load_lds_dwordx4 v[174:175], off
	s_waitcnt vmcnt(8)
	s_waitcnt lgkmcnt(0)
	s_barrier
	s_setprio 1
	s_waitcnt lgkmcnt(0)
	v_mfma_f32_16x16x32_bf16 v[130:133], v[134:137], v[186:189], v[130:133]
	v_mfma_f32_16x16x32_bf16 v[130:133], v[150:153], v[202:205], v[130:133]
	v_mfma_f32_16x16x32_bf16 v[126:129], v[154:157], v[186:189], v[126:129]
	v_mfma_f32_16x16x32_bf16 v[126:129], v[158:161], v[202:205], v[126:129]
	v_mfma_f32_16x16x32_bf16 v[114:117], v[134:137], v[206:209], v[114:117]
	v_mfma_f32_16x16x32_bf16 v[114:117], v[150:153], v[210:213], v[114:117]
	v_mfma_f32_16x16x32_bf16 v[110:113], v[154:157], v[206:209], v[110:113]
	v_mfma_f32_16x16x32_bf16 v[110:113], v[158:161], v[210:213], v[110:113]
	v_mfma_f32_16x16x32_bf16 v[98:101], v[134:137], v[214:217], v[98:101]
	v_mfma_f32_16x16x32_bf16 v[98:101], v[150:153], v[218:221], v[98:101]
	v_mfma_f32_16x16x32_bf16 v[94:97], v[154:157], v[214:217], v[94:97]
	v_mfma_f32_16x16x32_bf16 v[94:97], v[158:161], v[218:221], v[94:97]
	v_mfma_f32_16x16x32_bf16 v[82:85], v[134:137], v[222:225], v[82:85]
	v_mfma_f32_16x16x32_bf16 v[82:85], v[150:153], v[226:229], v[82:85]
	v_mfma_f32_16x16x32_bf16 v[78:81], v[154:157], v[222:225], v[78:81]
	v_mfma_f32_16x16x32_bf16 v[78:81], v[158:161], v[226:229], v[78:81]
	s_setprio 0
	s_setprio 1
	v_mfma_f32_16x16x32_bf16 v[122:125], v[162:165], v[186:189], v[122:125]
	v_mfma_f32_16x16x32_bf16 v[122:125], v[166:169], v[202:205], v[122:125]
	v_mfma_f32_16x16x32_bf16 v[118:121], v[170:173], v[186:189], v[118:121]
	v_mfma_f32_16x16x32_bf16 v[118:121], v[182:185], v[202:205], v[118:121]
	v_mfma_f32_16x16x32_bf16 v[106:109], v[162:165], v[206:209], v[106:109]
	v_mfma_f32_16x16x32_bf16 v[106:109], v[166:169], v[210:213], v[106:109]
	v_mfma_f32_16x16x32_bf16 v[102:105], v[170:173], v[206:209], v[102:105]
	v_mfma_f32_16x16x32_bf16 v[102:105], v[182:185], v[210:213], v[102:105]
	v_mfma_f32_16x16x32_bf16 v[90:93], v[162:165], v[214:217], v[90:93]
	v_mfma_f32_16x16x32_bf16 v[90:93], v[166:169], v[218:221], v[90:93]
	v_mfma_f32_16x16x32_bf16 v[86:89], v[170:173], v[214:217], v[86:89]
	v_mfma_f32_16x16x32_bf16 v[86:89], v[182:185], v[218:221], v[86:89]
	v_mfma_f32_16x16x32_bf16 v[74:77], v[162:165], v[222:225], v[74:77]
	v_mfma_f32_16x16x32_bf16 v[74:77], v[166:169], v[226:229], v[74:77]
	v_mfma_f32_16x16x32_bf16 v[70:73], v[170:173], v[222:225], v[70:73]
	v_mfma_f32_16x16x32_bf16 v[70:73], v[182:185], v[226:229], v[70:73]
	s_setprio 0
	s_barrier
	s_add_i32 s52, s52, s36
	v_lshl_add_u64 v[174:175], s[30:31], 0, v[0:1]
	s_mov_b32 m0, s52
	ds_read_b128 v[186:189], v201 offset:16384
	ds_read_b128 v[202:205], v201 offset:17408
	ds_read_b128 v[206:209], v201 offset:18432
	ds_read_b128 v[210:213], v201 offset:19456
	ds_read_b128 v[214:217], v201 offset:20480
	ds_read_b128 v[218:221], v201 offset:21504
	ds_read_b128 v[222:225], v201 offset:22528
	ds_read_b128 v[226:229], v201 offset:23552
	global_load_lds_dwordx4 v[174:175], off
	s_add_i32 m0, s52, 0x2000
	s_add_u32 s52, s30, 0x40000
	v_lshl_add_u64 v[190:191], s[30:31], 0, v[14:15]
	s_addc_u32 s53, s31, 0
	s_add_i32 s54, s54, s36
	global_load_lds_dwordx4 v[190:191], off
	v_lshl_add_u64 v[230:231], s[52:53], 0, v[0:1]
	s_mov_b32 m0, s54
	v_lshl_add_u64 v[232:233], s[34:35], 0, v[138:139]
	global_load_lds_dwordx4 v[230:231], off
	v_lshl_add_u64 v[230:231], s[52:53], 0, v[14:15]
	s_add_i32 m0, s54, 0x2000
	s_nop 0
	global_load_lds_dwordx4 v[230:231], off
	v_lshl_add_u64 v[230:231], s[34:35], 0, v[140:141]
	s_mov_b32 m0, s39
	s_nop 0
	global_load_lds_dwordx4 v[230:231], off
	s_mov_b32 m0, s40
	s_nop 0
	global_load_lds_dwordx4 v[232:233], off
	s_waitcnt vmcnt(8)
	s_waitcnt lgkmcnt(0)
	s_barrier
	s_setprio 1
	s_waitcnt lgkmcnt(0)
	v_mfma_f32_16x16x32_bf16 v[66:69], v[134:137], v[186:189], v[66:69]
	v_mfma_f32_16x16x32_bf16 v[66:69], v[150:153], v[202:205], v[66:69]
	v_mfma_f32_16x16x32_bf16 v[62:65], v[154:157], v[186:189], v[62:65]
	v_mfma_f32_16x16x32_bf16 v[62:65], v[158:161], v[202:205], v[62:65]
	v_mfma_f32_16x16x32_bf16 v[50:53], v[134:137], v[206:209], v[50:53]
	v_mfma_f32_16x16x32_bf16 v[50:53], v[150:153], v[210:213], v[50:53]
	v_mfma_f32_16x16x32_bf16 v[46:49], v[154:157], v[206:209], v[46:49]
	v_mfma_f32_16x16x32_bf16 v[46:49], v[158:161], v[210:213], v[46:49]
	v_mfma_f32_16x16x32_bf16 v[34:37], v[134:137], v[214:217], v[34:37]
	v_mfma_f32_16x16x32_bf16 v[34:37], v[150:153], v[218:221], v[34:37]
	v_mfma_f32_16x16x32_bf16 v[30:33], v[154:157], v[214:217], v[30:33]
	v_mfma_f32_16x16x32_bf16 v[30:33], v[158:161], v[218:221], v[30:33]
	v_mfma_f32_16x16x32_bf16 v[18:21], v[134:137], v[222:225], v[18:21]
	v_mfma_f32_16x16x32_bf16 v[18:21], v[150:153], v[226:229], v[18:21]
	v_mfma_f32_16x16x32_bf16 v[10:13], v[154:157], v[222:225], v[10:13]
	v_mfma_f32_16x16x32_bf16 v[10:13], v[158:161], v[226:229], v[10:13]
	s_setprio 0
	s_setprio 1
	v_mfma_f32_16x16x32_bf16 v[58:61], v[162:165], v[186:189], v[58:61]
	v_mfma_f32_16x16x32_bf16 v[58:61], v[166:169], v[202:205], v[58:61]
	v_mfma_f32_16x16x32_bf16 v[54:57], v[170:173], v[186:189], v[54:57]
	v_mfma_f32_16x16x32_bf16 v[54:57], v[182:185], v[202:205], v[54:57]
	v_mfma_f32_16x16x32_bf16 v[42:45], v[162:165], v[206:209], v[42:45]
	v_mfma_f32_16x16x32_bf16 v[42:45], v[166:169], v[210:213], v[42:45]
	v_mfma_f32_16x16x32_bf16 v[38:41], v[170:173], v[206:209], v[38:41]
	v_mfma_f32_16x16x32_bf16 v[38:41], v[182:185], v[210:213], v[38:41]
	v_mfma_f32_16x16x32_bf16 v[26:29], v[162:165], v[214:217], v[26:29]
	v_mfma_f32_16x16x32_bf16 v[26:29], v[166:169], v[218:221], v[26:29]
	v_mfma_f32_16x16x32_bf16 v[22:25], v[170:173], v[214:217], v[22:25]
	v_mfma_f32_16x16x32_bf16 v[22:25], v[182:185], v[218:221], v[22:25]
	v_mfma_f32_16x16x32_bf16 v[6:9], v[162:165], v[222:225], v[6:9]
	v_mfma_f32_16x16x32_bf16 v[6:9], v[166:169], v[226:229], v[6:9]
	v_mfma_f32_16x16x32_bf16 v[2:5], v[170:173], v[222:225], v[2:5]
	v_mfma_f32_16x16x32_bf16 v[2:5], v[182:185], v[226:229], v[2:5]
	s_setprio 0
	s_barrier
	s_add_i32 s52, 0, 0x18000
	s_add_i32 s53, 0, 0x1c000
	v_add_u32_e32 v158, s52, v199
	v_add_u32_e32 v182, s53, v199
	ds_read_b128 v[134:137], v158
	ds_read_b128 v[150:153], v158 offset:1024
	ds_read_b128 v[154:157], v158 offset:2048
	ds_read_b128 v[158:161], v158 offset:3072
	ds_read_b128 v[162:165], v182
	ds_read_b128 v[166:169], v182 offset:1024
	ds_read_b128 v[170:173], v182 offset:2048
	ds_read_b128 v[182:185], v182 offset:3072
	s_add_u32 s34, s34, 0x40000
	s_addc_u32 s35, s35, 0
	s_mov_b32 m0, s41
	v_lshl_add_u64 v[234:235], s[34:35], 0, v[140:141]
	ds_read_b128 v[186:189], v201 offset:32768
	ds_read_b128 v[202:205], v201 offset:33792
	ds_read_b128 v[206:209], v201 offset:34816
	ds_read_b128 v[210:213], v201 offset:35840
	ds_read_b128 v[214:217], v201 offset:36864
	ds_read_b128 v[218:221], v201 offset:37888
	ds_read_b128 v[222:225], v201 offset:38912
	ds_read_b128 v[226:229], v201 offset:39936
	global_load_lds_dwordx4 v[234:235], off
	v_lshl_add_u64 v[234:235], s[34:35], 0, v[138:139]
	s_mov_b32 m0, s42
	s_nop 0
	global_load_lds_dwordx4 v[234:235], off
	s_waitcnt vmcnt(8)
	s_waitcnt lgkmcnt(0)
	s_barrier
	s_setprio 1
	s_waitcnt lgkmcnt(0)
	v_mfma_f32_16x16x32_bf16 v[130:133], v[134:137], v[186:189], v[130:133]
	v_mfma_f32_16x16x32_bf16 v[130:133], v[150:153], v[202:205], v[130:133]
	v_mfma_f32_16x16x32_bf16 v[126:129], v[154:157], v[186:189], v[126:129]
	v_mfma_f32_16x16x32_bf16 v[126:129], v[158:161], v[202:205], v[126:129]
	v_mfma_f32_16x16x32_bf16 v[114:117], v[134:137], v[206:209], v[114:117]
	v_mfma_f32_16x16x32_bf16 v[114:117], v[150:153], v[210:213], v[114:117]
	v_mfma_f32_16x16x32_bf16 v[110:113], v[154:157], v[206:209], v[110:113]
	v_mfma_f32_16x16x32_bf16 v[110:113], v[158:161], v[210:213], v[110:113]
	v_mfma_f32_16x16x32_bf16 v[98:101], v[134:137], v[214:217], v[98:101]
	v_mfma_f32_16x16x32_bf16 v[98:101], v[150:153], v[218:221], v[98:101]
	v_mfma_f32_16x16x32_bf16 v[94:97], v[154:157], v[214:217], v[94:97]
	v_mfma_f32_16x16x32_bf16 v[94:97], v[158:161], v[218:221], v[94:97]
	v_mfma_f32_16x16x32_bf16 v[82:85], v[134:137], v[222:225], v[82:85]
	v_mfma_f32_16x16x32_bf16 v[82:85], v[150:153], v[226:229], v[82:85]
	v_mfma_f32_16x16x32_bf16 v[78:81], v[154:157], v[222:225], v[78:81]
	v_mfma_f32_16x16x32_bf16 v[78:81], v[158:161], v[226:229], v[78:81]
	s_setprio 0
	s_setprio 1
	v_mfma_f32_16x16x32_bf16 v[122:125], v[162:165], v[186:189], v[122:125]
	v_mfma_f32_16x16x32_bf16 v[122:125], v[166:169], v[202:205], v[122:125]
	v_mfma_f32_16x16x32_bf16 v[118:121], v[170:173], v[186:189], v[118:121]
	v_mfma_f32_16x16x32_bf16 v[118:121], v[182:185], v[202:205], v[118:121]
	v_mfma_f32_16x16x32_bf16 v[106:109], v[162:165], v[206:209], v[106:109]
	v_mfma_f32_16x16x32_bf16 v[106:109], v[166:169], v[210:213], v[106:109]
	v_mfma_f32_16x16x32_bf16 v[102:105], v[170:173], v[206:209], v[102:105]
	v_mfma_f32_16x16x32_bf16 v[102:105], v[182:185], v[210:213], v[102:105]
	v_mfma_f32_16x16x32_bf16 v[90:93], v[162:165], v[214:217], v[90:93]
	v_mfma_f32_16x16x32_bf16 v[90:93], v[166:169], v[218:221], v[90:93]
	v_mfma_f32_16x16x32_bf16 v[86:89], v[170:173], v[214:217], v[86:89]
	v_mfma_f32_16x16x32_bf16 v[86:89], v[182:185], v[218:221], v[86:89]
	v_mfma_f32_16x16x32_bf16 v[74:77], v[162:165], v[222:225], v[74:77]
	v_mfma_f32_16x16x32_bf16 v[74:77], v[166:169], v[226:229], v[74:77]
	v_mfma_f32_16x16x32_bf16 v[70:73], v[170:173], v[222:225], v[70:73]
	v_mfma_f32_16x16x32_bf16 v[70:73], v[182:185], v[226:229], v[70:73]
	s_setprio 0
	s_barrier
	s_add_i32 s34, s52, s36
	v_lshl_add_u64 v[174:175], v[174:175], 0, s[92:93]
	s_mov_b32 m0, s34
	ds_read_b128 v[186:189], v201 offset:49152
	ds_read_b128 v[202:205], v201 offset:50176
	ds_read_b128 v[206:209], v201 offset:51200
	ds_read_b128 v[210:213], v201 offset:52224
	ds_read_b128 v[214:217], v201 offset:53248
	ds_read_b128 v[218:221], v201 offset:54272
	ds_read_b128 v[222:225], v201 offset:55296
	ds_read_b128 v[226:229], v201 offset:56320
	global_load_lds_dwordx4 v[174:175], off
	s_add_i32 m0, s34, 0x2000
	s_add_u32 s30, s30, 0x40080
	v_lshl_add_u64 v[174:175], v[190:191], 0, s[92:93]
	s_addc_u32 s31, s31, 0
	s_add_i32 s34, s53, s36
	global_load_lds_dwordx4 v[174:175], off
	v_lshl_add_u64 v[174:175], s[30:31], 0, v[0:1]
	s_mov_b32 m0, s34
	s_nop 0
	global_load_lds_dwordx4 v[174:175], off
	v_lshl_add_u64 v[174:175], s[30:31], 0, v[14:15]
	s_add_i32 m0, s34, 0x2000
	s_nop 0
	global_load_lds_dwordx4 v[174:175], off
	v_lshl_add_u64 v[174:175], v[230:231], 0, s[92:93]
	s_mov_b32 m0, s43
	s_nop 0
	global_load_lds_dwordx4 v[174:175], off
	v_lshl_add_u64 v[174:175], v[232:233], 0, s[92:93]
	s_mov_b32 m0, s44
	s_nop 0
	global_load_lds_dwordx4 v[174:175], off
	s_waitcnt vmcnt(8)
	s_waitcnt lgkmcnt(0)
	s_barrier
	s_setprio 1
	s_waitcnt lgkmcnt(0)
	v_mfma_f32_16x16x32_bf16 v[66:69], v[134:137], v[186:189], v[66:69]
	v_mfma_f32_16x16x32_bf16 v[66:69], v[150:153], v[202:205], v[66:69]
	v_mfma_f32_16x16x32_bf16 v[62:65], v[154:157], v[186:189], v[62:65]
	v_mfma_f32_16x16x32_bf16 v[62:65], v[158:161], v[202:205], v[62:65]
	v_mfma_f32_16x16x32_bf16 v[50:53], v[134:137], v[206:209], v[50:53]
	v_mfma_f32_16x16x32_bf16 v[50:53], v[150:153], v[210:213], v[50:53]
	v_mfma_f32_16x16x32_bf16 v[46:49], v[154:157], v[206:209], v[46:49]
	v_mfma_f32_16x16x32_bf16 v[46:49], v[158:161], v[210:213], v[46:49]
	v_mfma_f32_16x16x32_bf16 v[34:37], v[134:137], v[214:217], v[34:37]
	v_mfma_f32_16x16x32_bf16 v[34:37], v[150:153], v[218:221], v[34:37]
	v_mfma_f32_16x16x32_bf16 v[30:33], v[154:157], v[214:217], v[30:33]
	v_mfma_f32_16x16x32_bf16 v[30:33], v[158:161], v[218:221], v[30:33]
	v_mfma_f32_16x16x32_bf16 v[18:21], v[134:137], v[222:225], v[18:21]
	v_mfma_f32_16x16x32_bf16 v[18:21], v[150:153], v[226:229], v[18:21]
	v_mfma_f32_16x16x32_bf16 v[10:13], v[154:157], v[222:225], v[10:13]
	v_mfma_f32_16x16x32_bf16 v[10:13], v[158:161], v[226:229], v[10:13]
	s_setprio 0
	s_setprio 1
	v_mfma_f32_16x16x32_bf16 v[58:61], v[162:165], v[186:189], v[58:61]
	v_mfma_f32_16x16x32_bf16 v[58:61], v[166:169], v[202:205], v[58:61]
	v_mfma_f32_16x16x32_bf16 v[54:57], v[170:173], v[186:189], v[54:57]
	v_mfma_f32_16x16x32_bf16 v[54:57], v[182:185], v[202:205], v[54:57]
	v_mfma_f32_16x16x32_bf16 v[42:45], v[162:165], v[206:209], v[42:45]
	v_mfma_f32_16x16x32_bf16 v[42:45], v[166:169], v[210:213], v[42:45]
	v_mfma_f32_16x16x32_bf16 v[38:41], v[170:173], v[206:209], v[38:41]
	v_mfma_f32_16x16x32_bf16 v[38:41], v[182:185], v[210:213], v[38:41]
	v_mfma_f32_16x16x32_bf16 v[26:29], v[162:165], v[214:217], v[26:29]
	v_mfma_f32_16x16x32_bf16 v[26:29], v[166:169], v[218:221], v[26:29]
	v_mfma_f32_16x16x32_bf16 v[22:25], v[170:173], v[214:217], v[22:25]
	v_mfma_f32_16x16x32_bf16 v[22:25], v[182:185], v[218:221], v[22:25]
	v_mfma_f32_16x16x32_bf16 v[6:9], v[162:165], v[222:225], v[6:9]
	v_mfma_f32_16x16x32_bf16 v[6:9], v[166:169], v[226:229], v[6:9]
	v_mfma_f32_16x16x32_bf16 v[2:5], v[170:173], v[222:225], v[2:5]
	v_mfma_f32_16x16x32_bf16 v[2:5], v[182:185], v[226:229], v[2:5]
	s_setprio 0
	s_barrier
	s_add_i32 s51, s51, 2
	s_add_u32 s0, s0, 0x100
	s_addc_u32 s1, s1, 0
	s_add_u32 s49, s49, 0x100
	s_addc_u32 s50, s50, 0
	s_cmp_gt_u32 s51, 13
	s_cbranch_scc0 .LBB0_566
.Lpeel_exit_1:
	s_and_b64 vcc, exec, s[18:19]
	s_cbranch_vccz .LBB0_569
	s_barrier

.LBB0_636:
	s_add_u32 s22, s22, 0x80
	s_addc_u32 s23, s23, 0
	s_add_u32 s45, s24, 0x100
	s_addc_u32 s46, s25, 0
	s_mov_b32 s24, 0
	s_add_i32 s47, s24, 2
	s_add_u32 s48, s22, 0x80
	s_addc_u32 s25, s23, 0
	s_add_i32 s50, 0, 0x10000
	s_cmp_eq_u32 s40, s24
	s_cselect_b32 s25, s7, s25
	s_cselect_b32 s24, s6, s48
	v_add_u32_e32 v135, s50, v249
	s_cselect_b32 s49, s21, s46
	s_cselect_b32 s48, s20, s45
	s_add_i32 s51, 0, 0x14000
	ds_read_b128 v[142:145], v135
	ds_read_b128 v[146:149], v135 offset:1024
	ds_read_b128 v[150:153], v135 offset:2048
	ds_read_b128 v[154:157], v135 offset:3072
	v_add_u32_e32 v135, s51, v249
	ds_read_b128 v[158:161], v135
	ds_read_b128 v[162:165], v135 offset:1024
	ds_read_b128 v[166:169], v135 offset:2048
	ds_read_b128 v[170:173], v135 offset:3072
	v_lshl_add_u64 v[174:175], s[22:23], 0, v[138:139]
	s_add_i32 m0, s31, 0xc000
	ds_read_b128 v[182:185], v251
	ds_read_b128 v[186:189], v251 offset:1024
	ds_read_b128 v[190:193], v251 offset:2048
	ds_read_b128 v[194:197], v251 offset:3072
	ds_read_b128 v[198:201], v251 offset:4096
	ds_read_b128 v[202:205], v251 offset:5120
	ds_read_b128 v[206:209], v251 offset:6144
	ds_read_b128 v[210:213], v251 offset:7168
	global_load_lds_dwordx4 v[174:175], off
	v_lshl_add_u64 v[174:175], s[22:23], 0, v[140:141]
	s_add_i32 m0, s31, 0xe000
	s_nop 0
	global_load_lds_dwordx4 v[174:175], off
	s_waitcnt vmcnt(8)
	s_waitcnt lgkmcnt(0)
	s_barrier
	s_setprio 1
	s_waitcnt lgkmcnt(0)
	v_mfma_f32_16x16x32_bf16 v[130:133], v[142:145], v[182:185], 0
	v_mfma_f32_16x16x32_bf16 v[130:133], v[146:149], v[186:189], v[130:133]
	v_mfma_f32_16x16x32_bf16 v[126:129], v[150:153], v[182:185], 0
	v_mfma_f32_16x16x32_bf16 v[126:129], v[154:157], v[186:189], v[126:129]
	v_mfma_f32_16x16x32_bf16 v[114:117], v[142:145], v[190:193], 0
	v_mfma_f32_16x16x32_bf16 v[114:117], v[146:149], v[194:197], v[114:117]
	v_mfma_f32_16x16x32_bf16 v[110:113], v[150:153], v[190:193], 0
	v_mfma_f32_16x16x32_bf16 v[110:113], v[154:157], v[194:197], v[110:113]
	v_mfma_f32_16x16x32_bf16 v[98:101], v[142:145], v[198:201], 0
	v_mfma_f32_16x16x32_bf16 v[98:101], v[146:149], v[202:205], v[98:101]
	v_mfma_f32_16x16x32_bf16 v[94:97], v[150:153], v[198:201], 0
	v_mfma_f32_16x16x32_bf16 v[94:97], v[154:157], v[202:205], v[94:97]
	v_mfma_f32_16x16x32_bf16 v[82:85], v[142:145], v[206:209], 0
	v_mfma_f32_16x16x32_bf16 v[82:85], v[146:149], v[210:213], v[82:85]
	v_mfma_f32_16x16x32_bf16 v[78:81], v[150:153], v[206:209], 0
	v_mfma_f32_16x16x32_bf16 v[78:81], v[154:157], v[210:213], v[78:81]
	s_setprio 0
	s_setprio 1
	v_mfma_f32_16x16x32_bf16 v[122:125], v[158:161], v[182:185], 0
	v_mfma_f32_16x16x32_bf16 v[122:125], v[162:165], v[186:189], v[122:125]
	v_mfma_f32_16x16x32_bf16 v[118:121], v[166:169], v[182:185], 0
	v_mfma_f32_16x16x32_bf16 v[118:121], v[170:173], v[186:189], v[118:121]
	v_mfma_f32_16x16x32_bf16 v[106:109], v[158:161], v[190:193], 0
	v_mfma_f32_16x16x32_bf16 v[106:109], v[162:165], v[194:197], v[106:109]
	v_mfma_f32_16x16x32_bf16 v[102:105], v[166:169], v[190:193], 0
	v_mfma_f32_16x16x32_bf16 v[102:105], v[170:173], v[194:197], v[102:105]
	v_mfma_f32_16x16x32_bf16 v[90:93], v[158:161], v[198:201], 0
	v_mfma_f32_16x16x32_bf16 v[90:93], v[162:165], v[202:205], v[90:93]
	v_mfma_f32_16x16x32_bf16 v[86:89], v[166:169], v[198:201], 0
	v_mfma_f32_16x16x32_bf16 v[86:89], v[170:173], v[202:205], v[86:89]
	v_mfma_f32_16x16x32_bf16 v[74:77], v[158:161], v[206:209], 0
	v_mfma_f32_16x16x32_bf16 v[74:77], v[162:165], v[210:213], v[74:77]
	v_mfma_f32_16x16x32_bf16 v[70:73], v[166:169], v[206:209], 0
	v_mfma_f32_16x16x32_bf16 v[70:73], v[170:173], v[210:213], v[70:73]
	s_setprio 0
	s_barrier
	s_add_i32 s50, s50, s30
	v_lshl_add_u64 v[174:175], s[48:49], 0, v[0:1]
	s_mov_b32 m0, s50
	ds_read_b128 v[182:185], v251 offset:16384
	ds_read_b128 v[186:189], v251 offset:17408
	ds_read_b128 v[190:193], v251 offset:18432
	ds_read_b128 v[194:197], v251 offset:19456
	ds_read_b128 v[198:201], v251 offset:20480
	ds_read_b128 v[202:205], v251 offset:21504
	ds_read_b128 v[206:209], v251 offset:22528
	ds_read_b128 v[210:213], v251 offset:23552
	global_load_lds_dwordx4 v[174:175], off
	s_add_i32 m0, s50, 0x2000
	v_lshl_add_u64 v[214:215], s[48:49], 0, v[14:15]
	s_add_u32 s48, s48, s10
	s_addc_u32 s49, s49, 0
	s_add_i32 s50, s51, s30
	global_load_lds_dwordx4 v[214:215], off
	v_lshl_add_u64 v[216:217], s[48:49], 0, v[0:1]
	s_mov_b32 m0, s50
	v_lshl_add_u64 v[218:219], s[48:49], 0, v[14:15]
	global_load_lds_dwordx4 v[216:217], off
	s_add_i32 m0, s50, 0x2000
	v_lshl_add_u64 v[220:221], s[24:25], 0, v[0:1]
	global_load_lds_dwordx4 v[218:219], off
	s_mov_b32 m0, s31
	v_lshl_add_u64 v[222:223], s[24:25], 0, v[14:15]
	global_load_lds_dwordx4 v[220:221], off
	s_mov_b32 m0, s34
	s_nop 0
	global_load_lds_dwordx4 v[222:223], off
	s_waitcnt vmcnt(8)
	s_waitcnt lgkmcnt(0)
	s_barrier
	s_setprio 1
	s_waitcnt lgkmcnt(0)
	v_mfma_f32_16x16x32_bf16 v[66:69], v[142:145], v[182:185], 0
	v_mfma_f32_16x16x32_bf16 v[66:69], v[146:149], v[186:189], v[66:69]
	v_mfma_f32_16x16x32_bf16 v[62:65], v[150:153], v[182:185], 0
	v_mfma_f32_16x16x32_bf16 v[62:65], v[154:157], v[186:189], v[62:65]
	v_mfma_f32_16x16x32_bf16 v[50:53], v[142:145], v[190:193], 0
	v_mfma_f32_16x16x32_bf16 v[50:53], v[146:149], v[194:197], v[50:53]
	v_mfma_f32_16x16x32_bf16 v[46:49], v[150:153], v[190:193], 0
	v_mfma_f32_16x16x32_bf16 v[46:49], v[154:157], v[194:197], v[46:49]
	v_mfma_f32_16x16x32_bf16 v[34:37], v[142:145], v[198:201], 0
	v_mfma_f32_16x16x32_bf16 v[34:37], v[146:149], v[202:205], v[34:37]
	v_mfma_f32_16x16x32_bf16 v[30:33], v[150:153], v[198:201], 0
	v_mfma_f32_16x16x32_bf16 v[30:33], v[154:157], v[202:205], v[30:33]
	v_mfma_f32_16x16x32_bf16 v[18:21], v[142:145], v[206:209], 0
	v_mfma_f32_16x16x32_bf16 v[18:21], v[146:149], v[210:213], v[18:21]
	v_mfma_f32_16x16x32_bf16 v[10:13], v[150:153], v[206:209], 0
	v_mfma_f32_16x16x32_bf16 v[10:13], v[154:157], v[210:213], v[10:13]
	s_setprio 0
	s_setprio 1
	v_mfma_f32_16x16x32_bf16 v[58:61], v[158:161], v[182:185], 0
	v_mfma_f32_16x16x32_bf16 v[58:61], v[162:165], v[186:189], v[58:61]
	v_mfma_f32_16x16x32_bf16 v[54:57], v[166:169], v[182:185], 0
	v_mfma_f32_16x16x32_bf16 v[54:57], v[170:173], v[186:189], v[54:57]
	v_mfma_f32_16x16x32_bf16 v[42:45], v[158:161], v[190:193], 0
	v_mfma_f32_16x16x32_bf16 v[42:45], v[162:165], v[194:197], v[42:45]
	v_mfma_f32_16x16x32_bf16 v[38:41], v[166:169], v[190:193], 0
	v_mfma_f32_16x16x32_bf16 v[38:41], v[170:173], v[194:197], v[38:41]
	v_mfma_f32_16x16x32_bf16 v[26:29], v[158:161], v[198:201], 0
	v_mfma_f32_16x16x32_bf16 v[26:29], v[162:165], v[202:205], v[26:29]
	v_mfma_f32_16x16x32_bf16 v[22:25], v[166:169], v[198:201], 0
	v_mfma_f32_16x16x32_bf16 v[22:25], v[170:173], v[202:205], v[22:25]
	v_mfma_f32_16x16x32_bf16 v[6:9], v[158:161], v[206:209], 0
	v_mfma_f32_16x16x32_bf16 v[6:9], v[162:165], v[210:213], v[6:9]
	v_mfma_f32_16x16x32_bf16 v[2:5], v[166:169], v[206:209], 0
	v_mfma_f32_16x16x32_bf16 v[2:5], v[170:173], v[210:213], v[2:5]
	s_setprio 0
	s_barrier
	s_add_i32 s48, 0, 0x18000
	v_add_u32_e32 v135, s48, v249
	s_add_i32 s49, 0, 0x1c000
	ds_read_b128 v[142:145], v135
	ds_read_b128 v[146:149], v135 offset:1024
	ds_read_b128 v[150:153], v135 offset:2048
	ds_read_b128 v[154:157], v135 offset:3072
	v_add_u32_e32 v135, s49, v249
	ds_read_b128 v[158:161], v135
	ds_read_b128 v[162:165], v135 offset:1024
	ds_read_b128 v[166:169], v135 offset:2048
	ds_read_b128 v[170:173], v135 offset:3072
	s_add_u32 s24, s24, s10
	s_addc_u32 s25, s25, 0
	s_mov_b32 m0, s35
	v_lshl_add_u64 v[224:225], s[24:25], 0, v[0:1]
	ds_read_b128 v[182:185], v251 offset:32768
	ds_read_b128 v[186:189], v251 offset:33792
	ds_read_b128 v[190:193], v251 offset:34816
	ds_read_b128 v[194:197], v251 offset:35840
	ds_read_b128 v[198:201], v251 offset:36864
	ds_read_b128 v[202:205], v251 offset:37888
	ds_read_b128 v[206:209], v251 offset:38912
	ds_read_b128 v[210:213], v251 offset:39936
	global_load_lds_dwordx4 v[224:225], off
	v_lshl_add_u64 v[224:225], s[24:25], 0, v[14:15]
	s_mov_b32 m0, s36
	s_nop 0
	global_load_lds_dwordx4 v[224:225], off
	s_waitcnt vmcnt(8)
	s_waitcnt lgkmcnt(0)
	s_barrier
	s_setprio 1
	s_waitcnt lgkmcnt(0)
	v_mfma_f32_16x16x32_bf16 v[130:133], v[142:145], v[182:185], v[130:133]
	v_mfma_f32_16x16x32_bf16 v[130:133], v[146:149], v[186:189], v[130:133]
	v_mfma_f32_16x16x32_bf16 v[126:129], v[150:153], v[182:185], v[126:129]
	v_mfma_f32_16x16x32_bf16 v[126:129], v[154:157], v[186:189], v[126:129]
	v_mfma_f32_16x16x32_bf16 v[114:117], v[142:145], v[190:193], v[114:117]
	v_mfma_f32_16x16x32_bf16 v[114:117], v[146:149], v[194:197], v[114:117]
	v_mfma_f32_16x16x32_bf16 v[110:113], v[150:153], v[190:193], v[110:113]
	v_mfma_f32_16x16x32_bf16 v[110:113], v[154:157], v[194:197], v[110:113]
	v_mfma_f32_16x16x32_bf16 v[98:101], v[142:145], v[198:201], v[98:101]
	v_mfma_f32_16x16x32_bf16 v[98:101], v[146:149], v[202:205], v[98:101]
	v_mfma_f32_16x16x32_bf16 v[94:97], v[150:153], v[198:201], v[94:97]
	v_mfma_f32_16x16x32_bf16 v[94:97], v[154:157], v[202:205], v[94:97]
	v_mfma_f32_16x16x32_bf16 v[82:85], v[142:145], v[206:209], v[82:85]
	v_mfma_f32_16x16x32_bf16 v[82:85], v[146:149], v[210:213], v[82:85]
	v_mfma_f32_16x16x32_bf16 v[78:81], v[150:153], v[206:209], v[78:81]
	v_mfma_f32_16x16x32_bf16 v[78:81], v[154:157], v[210:213], v[78:81]
	s_setprio 0
	s_setprio 1
	v_mfma_f32_16x16x32_bf16 v[122:125], v[158:161], v[182:185], v[122:125]
	v_mfma_f32_16x16x32_bf16 v[122:125], v[162:165], v[186:189], v[122:125]
	v_mfma_f32_16x16x32_bf16 v[118:121], v[166:169], v[182:185], v[118:121]
	v_mfma_f32_16x16x32_bf16 v[118:121], v[170:173], v[186:189], v[118:121]
	v_mfma_f32_16x16x32_bf16 v[106:109], v[158:161], v[190:193], v[106:109]
	v_mfma_f32_16x16x32_bf16 v[106:109], v[162:165], v[194:197], v[106:109]
	v_mfma_f32_16x16x32_bf16 v[102:105], v[166:169], v[190:193], v[102:105]
	v_mfma_f32_16x16x32_bf16 v[102:105], v[170:173], v[194:197], v[102:105]
	v_mfma_f32_16x16x32_bf16 v[90:93], v[158:161], v[198:201], v[90:93]
	v_mfma_f32_16x16x32_bf16 v[90:93], v[162:165], v[202:205], v[90:93]
	v_mfma_f32_16x16x32_bf16 v[86:89], v[166:169], v[198:201], v[86:89]
	v_mfma_f32_16x16x32_bf16 v[86:89], v[170:173], v[202:205], v[86:89]
	v_mfma_f32_16x16x32_bf16 v[74:77], v[158:161], v[206:209], v[74:77]
	v_mfma_f32_16x16x32_bf16 v[74:77], v[162:165], v[210:213], v[74:77]
	v_mfma_f32_16x16x32_bf16 v[70:73], v[166:169], v[206:209], v[70:73]
	v_mfma_f32_16x16x32_bf16 v[70:73], v[170:173], v[210:213], v[70:73]
	s_setprio 0
	s_barrier
	s_add_i32 s24, s48, s30
	v_lshl_add_u64 v[174:175], v[174:175], 0, s[92:93]
	s_mov_b32 m0, s24
	ds_read_b128 v[182:185], v251 offset:49152
	ds_read_b128 v[186:189], v251 offset:50176
	ds_read_b128 v[190:193], v251 offset:51200
	ds_read_b128 v[194:197], v251 offset:52224
	ds_read_b128 v[198:201], v251 offset:53248
	ds_read_b128 v[202:205], v251 offset:54272
	ds_read_b128 v[206:209], v251 offset:55296
	ds_read_b128 v[210:213], v251 offset:56320
	global_load_lds_dwordx4 v[174:175], off
	v_lshl_add_u64 v[174:175], v[214:215], 0, s[92:93]
	s_add_i32 m0, s24, 0x2000
	s_add_i32 s24, s49, s30
	global_load_lds_dwordx4 v[174:175], off
	v_lshl_add_u64 v[174:175], v[216:217], 0, s[92:93]
	s_mov_b32 m0, s24
	s_nop 0
	global_load_lds_dwordx4 v[174:175], off
	v_lshl_add_u64 v[174:175], v[218:219], 0, s[92:93]
	s_add_i32 m0, s24, 0x2000
	s_nop 0
	global_load_lds_dwordx4 v[174:175], off
	v_lshl_add_u64 v[174:175], v[220:221], 0, s[92:93]
	s_mov_b32 m0, s37
	s_nop 0
	global_load_lds_dwordx4 v[174:175], off
	v_lshl_add_u64 v[174:175], v[222:223], 0, s[92:93]
	s_mov_b32 m0, s38
	s_nop 0
	global_load_lds_dwordx4 v[174:175], off
	s_waitcnt vmcnt(8)
	s_waitcnt lgkmcnt(0)
	s_barrier
	s_setprio 1
	s_waitcnt lgkmcnt(0)
	v_mfma_f32_16x16x32_bf16 v[66:69], v[142:145], v[182:185], v[66:69]
	v_mfma_f32_16x16x32_bf16 v[66:69], v[146:149], v[186:189], v[66:69]
	v_mfma_f32_16x16x32_bf16 v[62:65], v[150:153], v[182:185], v[62:65]
	v_mfma_f32_16x16x32_bf16 v[62:65], v[154:157], v[186:189], v[62:65]
	v_mfma_f32_16x16x32_bf16 v[50:53], v[142:145], v[190:193], v[50:53]
	v_mfma_f32_16x16x32_bf16 v[50:53], v[146:149], v[194:197], v[50:53]
	v_mfma_f32_16x16x32_bf16 v[46:49], v[150:153], v[190:193], v[46:49]
	v_mfma_f32_16x16x32_bf16 v[46:49], v[154:157], v[194:197], v[46:49]
	v_mfma_f32_16x16x32_bf16 v[34:37], v[142:145], v[198:201], v[34:37]
	v_mfma_f32_16x16x32_bf16 v[34:37], v[146:149], v[202:205], v[34:37]
	v_mfma_f32_16x16x32_bf16 v[30:33], v[150:153], v[198:201], v[30:33]
	v_mfma_f32_16x16x32_bf16 v[30:33], v[154:157], v[202:205], v[30:33]
	v_mfma_f32_16x16x32_bf16 v[18:21], v[142:145], v[206:209], v[18:21]
	v_mfma_f32_16x16x32_bf16 v[18:21], v[146:149], v[210:213], v[18:21]
	v_mfma_f32_16x16x32_bf16 v[10:13], v[150:153], v[206:209], v[10:13]
	v_mfma_f32_16x16x32_bf16 v[10:13], v[154:157], v[210:213], v[10:13]
	s_setprio 0
	s_setprio 1
	v_mfma_f32_16x16x32_bf16 v[58:61], v[158:161], v[182:185], v[58:61]
	v_mfma_f32_16x16x32_bf16 v[58:61], v[162:165], v[186:189], v[58:61]
	v_mfma_f32_16x16x32_bf16 v[54:57], v[166:169], v[182:185], v[54:57]
	v_mfma_f32_16x16x32_bf16 v[54:57], v[170:173], v[186:189], v[54:57]
	v_mfma_f32_16x16x32_bf16 v[42:45], v[158:161], v[190:193], v[42:45]
	v_mfma_f32_16x16x32_bf16 v[42:45], v[162:165], v[194:197], v[42:45]
	v_mfma_f32_16x16x32_bf16 v[38:41], v[166:169], v[190:193], v[38:41]
	v_mfma_f32_16x16x32_bf16 v[38:41], v[170:173], v[194:197], v[38:41]
	v_mfma_f32_16x16x32_bf16 v[26:29], v[158:161], v[198:201], v[26:29]
	v_mfma_f32_16x16x32_bf16 v[26:29], v[162:165], v[202:205], v[26:29]
	v_mfma_f32_16x16x32_bf16 v[22:25], v[166:169], v[198:201], v[22:25]
	v_mfma_f32_16x16x32_bf16 v[22:25], v[170:173], v[202:205], v[22:25]
	v_mfma_f32_16x16x32_bf16 v[6:9], v[158:161], v[206:209], v[6:9]
	v_mfma_f32_16x16x32_bf16 v[6:9], v[162:165], v[210:213], v[6:9]
	v_mfma_f32_16x16x32_bf16 v[2:5], v[166:169], v[206:209], v[2:5]
	v_mfma_f32_16x16x32_bf16 v[2:5], v[170:173], v[210:213], v[2:5]
	s_setprio 0
	s_barrier
	s_add_u32 s22, s22, 0x100
	s_addc_u32 s23, s23, 0
	s_add_u32 s45, s45, 0x100
	s_addc_u32 s46, s46, 0
	s_cmp_ge_u32 s47, s39
	s_mov_b32 s24, s47
	s_cbranch_scc1 .Lpeel_exit_2

.LBB0_892:
	s_ashr_i32 s15, s14, 31
	s_lshl_b64 s[16:17], s[14:15], 19
	s_add_u32 s16, s84, s16
	s_addc_u32 s17, s85, s17
	s_and_b64 s[18:19], s[0:1], exec
	s_cselect_b32 s15, s17, s5
	s_cselect_b32 s36, s16, s4
	s_ashr_i32 s11, s10, 31
	s_lshl_b64 s[18:19], s[10:11], 19
	s_add_u32 s18, s24, s18
	s_addc_u32 s19, s25, s19
	s_and_b64 s[22:23], s[0:1], exec
	s_cselect_b32 s11, s19, s21
	s_cselect_b32 s37, s18, s20
	s_add_u32 s4, s4, 0x40080
	s_addc_u32 s5, s5, 0
	s_add_u32 s38, s20, 0x100
	s_addc_u32 s39, s21, 0
	s_mov_b32 s40, -2
	s_add_u32 s20, s4, 0xfffc0080
	s_addc_u32 s21, s5, -1
	s_add_i32 s41, 0, 0x10000
	s_cmp_eq_u32 s40, 12
	s_cselect_b32 s23, s15, s21
	s_cselect_b32 s22, s36, s20
	s_cselect_b32 s21, s11, s39
	s_cselect_b32 s20, s37, s38
	s_add_i32 s44, 0, 0x14000
	v_add_u32_e32 v156, s41, v171
	v_add_u32_e32 v164, s44, v171
	ds_read_b128 v[134:137], v156
	ds_read_b128 v[148:151], v156 offset:1024
	ds_read_b128 v[152:155], v156 offset:2048
	ds_read_b128 v[156:159], v156 offset:3072
	ds_read_b128 v[160:163], v164
	ds_read_b128 v[182:185], v164 offset:1024
	ds_read_b128 v[186:189], v164 offset:2048
	ds_read_b128 v[190:193], v164 offset:3072
	v_lshl_add_u64 v[226:227], s[4:5], 0, v[144:145]
	s_add_i32 m0, s26, 0xc000
	ds_read_b128 v[194:197], v175
	ds_read_b128 v[198:201], v175 offset:1024
	ds_read_b128 v[202:205], v175 offset:2048
	ds_read_b128 v[206:209], v175 offset:3072
	ds_read_b128 v[210:213], v175 offset:4096
	ds_read_b128 v[214:217], v175 offset:5120
	ds_read_b128 v[218:221], v175 offset:6144
	ds_read_b128 v[222:225], v175 offset:7168
	global_load_lds_dwordx4 v[226:227], off
	v_lshl_add_u64 v[226:227], s[4:5], 0, v[146:147]
	s_add_i32 m0, s26, 0xe000
	s_nop 0
	global_load_lds_dwordx4 v[226:227], off
	s_cmp_eq_i32 s40, -2
	s_cselect_b32 s98, s2, 0
	s_cmp_lg_u32 s98, 0
	s_cbranch_scc1 .Lg3_relax_w1_pl3
	s_waitcnt vmcnt(8)
	s_branch .Lg3_join_w1_pl3

.Lg3_join_w1_pl3:
	s_waitcnt lgkmcnt(0)
	s_barrier
	s_setprio 1
	s_waitcnt lgkmcnt(0)
	v_mfma_f32_16x16x32_bf16 v[130:133], v[134:137], v[194:197], 0
	v_mfma_f32_16x16x32_bf16 v[130:133], v[148:151], v[198:201], v[130:133]
	v_mfma_f32_16x16x32_bf16 v[122:125], v[152:155], v[194:197], 0
	v_mfma_f32_16x16x32_bf16 v[122:125], v[156:159], v[198:201], v[122:125]
	v_mfma_f32_16x16x32_bf16 v[114:117], v[134:137], v[202:205], 0
	v_mfma_f32_16x16x32_bf16 v[114:117], v[148:151], v[206:209], v[114:117]
	v_mfma_f32_16x16x32_bf16 v[106:109], v[152:155], v[202:205], 0
	v_mfma_f32_16x16x32_bf16 v[106:109], v[156:159], v[206:209], v[106:109]
	v_mfma_f32_16x16x32_bf16 v[98:101], v[134:137], v[210:213], 0
	v_mfma_f32_16x16x32_bf16 v[98:101], v[148:151], v[214:217], v[98:101]
	v_mfma_f32_16x16x32_bf16 v[90:93], v[152:155], v[210:213], 0
	v_mfma_f32_16x16x32_bf16 v[90:93], v[156:159], v[214:217], v[90:93]
	v_mfma_f32_16x16x32_bf16 v[82:85], v[134:137], v[218:221], 0
	v_mfma_f32_16x16x32_bf16 v[82:85], v[148:151], v[222:225], v[82:85]
	v_mfma_f32_16x16x32_bf16 v[74:77], v[152:155], v[218:221], 0
	v_mfma_f32_16x16x32_bf16 v[74:77], v[156:159], v[222:225], v[74:77]
	s_setprio 0
	s_setprio 1
	v_mfma_f32_16x16x32_bf16 v[126:129], v[160:163], v[194:197], 0
	v_mfma_f32_16x16x32_bf16 v[126:129], v[182:185], v[198:201], v[126:129]
	v_mfma_f32_16x16x32_bf16 v[118:121], v[186:189], v[194:197], 0
	v_mfma_f32_16x16x32_bf16 v[118:121], v[190:193], v[198:201], v[118:121]
	v_mfma_f32_16x16x32_bf16 v[110:113], v[160:163], v[202:205], 0
	v_mfma_f32_16x16x32_bf16 v[110:113], v[182:185], v[206:209], v[110:113]
	v_mfma_f32_16x16x32_bf16 v[102:105], v[186:189], v[202:205], 0
	v_mfma_f32_16x16x32_bf16 v[102:105], v[190:193], v[206:209], v[102:105]
	v_mfma_f32_16x16x32_bf16 v[94:97], v[160:163], v[210:213], 0
	v_mfma_f32_16x16x32_bf16 v[94:97], v[182:185], v[214:217], v[94:97]
	v_mfma_f32_16x16x32_bf16 v[86:89], v[186:189], v[210:213], 0
	v_mfma_f32_16x16x32_bf16 v[86:89], v[190:193], v[214:217], v[86:89]
	v_mfma_f32_16x16x32_bf16 v[78:81], v[160:163], v[218:221], 0
	v_mfma_f32_16x16x32_bf16 v[78:81], v[182:185], v[222:225], v[78:81]
	v_mfma_f32_16x16x32_bf16 v[70:73], v[186:189], v[218:221], 0
	v_mfma_f32_16x16x32_bf16 v[70:73], v[190:193], v[222:225], v[70:73]
	s_setprio 0
	s_barrier
	s_add_i32 s41, s41, s13
	v_lshl_add_u64 v[226:227], s[20:21], 0, v[0:1]
	s_mov_b32 m0, s41
	ds_read_b128 v[194:197], v175 offset:16384
	ds_read_b128 v[198:201], v175 offset:17408
	ds_read_b128 v[202:205], v175 offset:18432
	ds_read_b128 v[206:209], v175 offset:19456
	ds_read_b128 v[210:213], v175 offset:20480
	ds_read_b128 v[214:217], v175 offset:21504
	ds_read_b128 v[218:221], v175 offset:22528
	ds_read_b128 v[222:225], v175 offset:23552
	global_load_lds_dwordx4 v[226:227], off
	s_add_i32 m0, s41, 0x2000
	s_add_u32 s42, s20, 0x40000
	v_lshl_add_u64 v[228:229], s[20:21], 0, v[14:15]
	s_addc_u32 s43, s21, 0
	s_add_i32 s41, s44, s13
	global_load_lds_dwordx4 v[228:229], off
	v_lshl_add_u64 v[230:231], s[42:43], 0, v[0:1]
	s_mov_b32 m0, s41
	v_lshl_add_u64 v[232:233], s[22:23], 0, v[138:139]
	global_load_lds_dwordx4 v[230:231], off
	v_lshl_add_u64 v[230:231], s[42:43], 0, v[14:15]
	s_add_i32 m0, s41, 0x2000
	s_nop 0
	global_load_lds_dwordx4 v[230:231], off
	v_lshl_add_u64 v[230:231], s[22:23], 0, v[140:141]
	s_mov_b32 m0, s26
	s_nop 0
	global_load_lds_dwordx4 v[230:231], off
	s_mov_b32 m0, s27
	s_nop 0
	global_load_lds_dwordx4 v[232:233], off
	s_cmp_eq_i32 s40, -2
	s_cselect_b32 s98, s2, 0
	s_cmp_lg_u32 s98, 0
	s_cbranch_scc1 .Lg3_relax_w2_pl3
	s_waitcnt vmcnt(8)
	s_branch .Lg3_join_w2_pl3

.Lg3_join_w2_pl3:
	s_waitcnt lgkmcnt(0)
	s_barrier
	s_setprio 1
	s_waitcnt lgkmcnt(0)
	v_mfma_f32_16x16x32_bf16 v[66:69], v[134:137], v[194:197], 0
	v_mfma_f32_16x16x32_bf16 v[66:69], v[148:151], v[198:201], v[66:69]
	v_mfma_f32_16x16x32_bf16 v[58:61], v[152:155], v[194:197], 0
	v_mfma_f32_16x16x32_bf16 v[58:61], v[156:159], v[198:201], v[58:61]
	v_mfma_f32_16x16x32_bf16 v[50:53], v[134:137], v[202:205], 0
	v_mfma_f32_16x16x32_bf16 v[50:53], v[148:151], v[206:209], v[50:53]
	v_mfma_f32_16x16x32_bf16 v[42:45], v[152:155], v[202:205], 0
	v_mfma_f32_16x16x32_bf16 v[42:45], v[156:159], v[206:209], v[42:45]
	v_mfma_f32_16x16x32_bf16 v[34:37], v[134:137], v[210:213], 0
	v_mfma_f32_16x16x32_bf16 v[34:37], v[148:151], v[214:217], v[34:37]
	v_mfma_f32_16x16x32_bf16 v[26:29], v[152:155], v[210:213], 0
	v_mfma_f32_16x16x32_bf16 v[26:29], v[156:159], v[214:217], v[26:29]
	v_mfma_f32_16x16x32_bf16 v[18:21], v[134:137], v[218:221], 0
	v_mfma_f32_16x16x32_bf16 v[18:21], v[148:151], v[222:225], v[18:21]
	v_mfma_f32_16x16x32_bf16 v[6:9], v[152:155], v[218:221], 0
	v_mfma_f32_16x16x32_bf16 v[6:9], v[156:159], v[222:225], v[6:9]
	s_setprio 0
	s_setprio 1
	v_mfma_f32_16x16x32_bf16 v[62:65], v[160:163], v[194:197], 0
	v_mfma_f32_16x16x32_bf16 v[62:65], v[182:185], v[198:201], v[62:65]
	v_mfma_f32_16x16x32_bf16 v[54:57], v[186:189], v[194:197], 0
	v_mfma_f32_16x16x32_bf16 v[54:57], v[190:193], v[198:201], v[54:57]
	v_mfma_f32_16x16x32_bf16 v[46:49], v[160:163], v[202:205], 0
	v_mfma_f32_16x16x32_bf16 v[46:49], v[182:185], v[206:209], v[46:49]
	v_mfma_f32_16x16x32_bf16 v[38:41], v[186:189], v[202:205], 0
	v_mfma_f32_16x16x32_bf16 v[38:41], v[190:193], v[206:209], v[38:41]
	v_mfma_f32_16x16x32_bf16 v[30:33], v[160:163], v[210:213], 0
	v_mfma_f32_16x16x32_bf16 v[30:33], v[182:185], v[214:217], v[30:33]
	v_mfma_f32_16x16x32_bf16 v[22:25], v[186:189], v[210:213], 0
	v_mfma_f32_16x16x32_bf16 v[22:25], v[190:193], v[214:217], v[22:25]
	v_mfma_f32_16x16x32_bf16 v[10:13], v[160:163], v[218:221], 0
	v_mfma_f32_16x16x32_bf16 v[10:13], v[182:185], v[222:225], v[10:13]
	v_mfma_f32_16x16x32_bf16 v[2:5], v[186:189], v[218:221], 0
	v_mfma_f32_16x16x32_bf16 v[2:5], v[190:193], v[222:225], v[2:5]
	s_setprio 0
	s_barrier
	s_add_i32 s41, 0, 0x18000
	s_add_i32 s42, 0, 0x1c000
	v_add_u32_e32 v156, s41, v171
	v_add_u32_e32 v164, s42, v171
	ds_read_b128 v[134:137], v156
	ds_read_b128 v[148:151], v156 offset:1024
	ds_read_b128 v[152:155], v156 offset:2048
	ds_read_b128 v[156:159], v156 offset:3072
	ds_read_b128 v[160:163], v164
	ds_read_b128 v[182:185], v164 offset:1024
	ds_read_b128 v[186:189], v164 offset:2048
	ds_read_b128 v[190:193], v164 offset:3072
	s_add_u32 s22, s22, 0x40000
	s_addc_u32 s23, s23, 0
	s_mov_b32 m0, s28
	v_lshl_add_u64 v[234:235], s[22:23], 0, v[140:141]
	ds_read_b128 v[194:197], v175 offset:32768
	ds_read_b128 v[198:201], v175 offset:33792
	ds_read_b128 v[202:205], v175 offset:34816
	ds_read_b128 v[206:209], v175 offset:35840
	ds_read_b128 v[210:213], v175 offset:36864
	ds_read_b128 v[214:217], v175 offset:37888
	ds_read_b128 v[218:221], v175 offset:38912
	ds_read_b128 v[222:225], v175 offset:39936
	global_load_lds_dwordx4 v[234:235], off
	v_lshl_add_u64 v[234:235], s[22:23], 0, v[138:139]
	s_mov_b32 m0, s29
	s_nop 0
	global_load_lds_dwordx4 v[234:235], off
	s_waitcnt vmcnt(8)
	s_waitcnt lgkmcnt(0)
	s_barrier
	s_setprio 1
	s_waitcnt lgkmcnt(0)
	v_mfma_f32_16x16x32_bf16 v[130:133], v[134:137], v[194:197], v[130:133]
	v_mfma_f32_16x16x32_bf16 v[130:133], v[148:151], v[198:201], v[130:133]
	v_mfma_f32_16x16x32_bf16 v[122:125], v[152:155], v[194:197], v[122:125]
	v_mfma_f32_16x16x32_bf16 v[122:125], v[156:159], v[198:201], v[122:125]
	v_mfma_f32_16x16x32_bf16 v[114:117], v[134:137], v[202:205], v[114:117]
	v_mfma_f32_16x16x32_bf16 v[114:117], v[148:151], v[206:209], v[114:117]
	v_mfma_f32_16x16x32_bf16 v[106:109], v[152:155], v[202:205], v[106:109]
	v_mfma_f32_16x16x32_bf16 v[106:109], v[156:159], v[206:209], v[106:109]
	v_mfma_f32_16x16x32_bf16 v[98:101], v[134:137], v[210:213], v[98:101]
	v_mfma_f32_16x16x32_bf16 v[98:101], v[148:151], v[214:217], v[98:101]
	v_mfma_f32_16x16x32_bf16 v[90:93], v[152:155], v[210:213], v[90:93]
	v_mfma_f32_16x16x32_bf16 v[90:93], v[156:159], v[214:217], v[90:93]
	v_mfma_f32_16x16x32_bf16 v[82:85], v[134:137], v[218:221], v[82:85]
	v_mfma_f32_16x16x32_bf16 v[82:85], v[148:151], v[222:225], v[82:85]
	v_mfma_f32_16x16x32_bf16 v[74:77], v[152:155], v[218:221], v[74:77]
	v_mfma_f32_16x16x32_bf16 v[74:77], v[156:159], v[222:225], v[74:77]
	s_setprio 0
	s_setprio 1
	v_mfma_f32_16x16x32_bf16 v[126:129], v[160:163], v[194:197], v[126:129]
	v_mfma_f32_16x16x32_bf16 v[126:129], v[182:185], v[198:201], v[126:129]
	v_mfma_f32_16x16x32_bf16 v[118:121], v[186:189], v[194:197], v[118:121]
	v_mfma_f32_16x16x32_bf16 v[118:121], v[190:193], v[198:201], v[118:121]
	v_mfma_f32_16x16x32_bf16 v[110:113], v[160:163], v[202:205], v[110:113]
	v_mfma_f32_16x16x32_bf16 v[110:113], v[182:185], v[206:209], v[110:113]
	v_mfma_f32_16x16x32_bf16 v[102:105], v[186:189], v[202:205], v[102:105]
	v_mfma_f32_16x16x32_bf16 v[102:105], v[190:193], v[206:209], v[102:105]
	v_mfma_f32_16x16x32_bf16 v[94:97], v[160:163], v[210:213], v[94:97]
	v_mfma_f32_16x16x32_bf16 v[94:97], v[182:185], v[214:217], v[94:97]
	v_mfma_f32_16x16x32_bf16 v[86:89], v[186:189], v[210:213], v[86:89]
	v_mfma_f32_16x16x32_bf16 v[86:89], v[190:193], v[214:217], v[86:89]
	v_mfma_f32_16x16x32_bf16 v[78:81], v[160:163], v[218:221], v[78:81]
	v_mfma_f32_16x16x32_bf16 v[78:81], v[182:185], v[222:225], v[78:81]
	v_mfma_f32_16x16x32_bf16 v[70:73], v[186:189], v[218:221], v[70:73]
	v_mfma_f32_16x16x32_bf16 v[70:73], v[190:193], v[222:225], v[70:73]
	s_setprio 0
	s_barrier
	s_add_i32 s22, s41, s13
	v_lshl_add_u64 v[226:227], v[226:227], 0, s[92:93]
	s_mov_b32 m0, s22
	ds_read_b128 v[194:197], v175 offset:49152
	ds_read_b128 v[198:201], v175 offset:50176
	ds_read_b128 v[202:205], v175 offset:51200
	ds_read_b128 v[206:209], v175 offset:52224
	ds_read_b128 v[210:213], v175 offset:53248
	ds_read_b128 v[214:217], v175 offset:54272
	ds_read_b128 v[218:221], v175 offset:55296
	ds_read_b128 v[222:225], v175 offset:56320
	global_load_lds_dwordx4 v[226:227], off
	s_add_i32 m0, s22, 0x2000
	s_add_u32 s20, s20, 0x40080
	v_lshl_add_u64 v[226:227], v[228:229], 0, s[92:93]
	s_addc_u32 s21, s21, 0
	s_add_i32 s22, s42, s13
	global_load_lds_dwordx4 v[226:227], off
	v_lshl_add_u64 v[226:227], s[20:21], 0, v[0:1]
	s_mov_b32 m0, s22
	s_nop 0
	global_load_lds_dwordx4 v[226:227], off
	v_lshl_add_u64 v[226:227], s[20:21], 0, v[14:15]
	s_add_i32 m0, s22, 0x2000
	s_nop 0
	global_load_lds_dwordx4 v[226:227], off
	v_lshl_add_u64 v[226:227], v[230:231], 0, s[92:93]
	s_mov_b32 m0, s30
	s_nop 0
	global_load_lds_dwordx4 v[226:227], off
	v_lshl_add_u64 v[226:227], v[232:233], 0, s[92:93]
	s_mov_b32 m0, s31
	s_nop 0
	global_load_lds_dwordx4 v[226:227], off
	s_waitcnt vmcnt(8)
	s_waitcnt lgkmcnt(0)
	s_barrier
	s_setprio 1
	s_waitcnt lgkmcnt(0)
	v_mfma_f32_16x16x32_bf16 v[66:69], v[134:137], v[194:197], v[66:69]
	v_mfma_f32_16x16x32_bf16 v[66:69], v[148:151], v[198:201], v[66:69]
	v_mfma_f32_16x16x32_bf16 v[58:61], v[152:155], v[194:197], v[58:61]
	v_mfma_f32_16x16x32_bf16 v[58:61], v[156:159], v[198:201], v[58:61]
	v_mfma_f32_16x16x32_bf16 v[50:53], v[134:137], v[202:205], v[50:53]
	v_mfma_f32_16x16x32_bf16 v[50:53], v[148:151], v[206:209], v[50:53]
	v_mfma_f32_16x16x32_bf16 v[42:45], v[152:155], v[202:205], v[42:45]
	v_mfma_f32_16x16x32_bf16 v[42:45], v[156:159], v[206:209], v[42:45]
	v_mfma_f32_16x16x32_bf16 v[34:37], v[134:137], v[210:213], v[34:37]
	v_mfma_f32_16x16x32_bf16 v[34:37], v[148:151], v[214:217], v[34:37]
	v_mfma_f32_16x16x32_bf16 v[26:29], v[152:155], v[210:213], v[26:29]
	v_mfma_f32_16x16x32_bf16 v[26:29], v[156:159], v[214:217], v[26:29]
	v_mfma_f32_16x16x32_bf16 v[18:21], v[134:137], v[218:221], v[18:21]
	v_mfma_f32_16x16x32_bf16 v[18:21], v[148:151], v[222:225], v[18:21]
	v_mfma_f32_16x16x32_bf16 v[6:9], v[152:155], v[218:221], v[6:9]
	v_mfma_f32_16x16x32_bf16 v[6:9], v[156:159], v[222:225], v[6:9]
	s_setprio 0
	s_setprio 1
	v_mfma_f32_16x16x32_bf16 v[62:65], v[160:163], v[194:197], v[62:65]
	v_mfma_f32_16x16x32_bf16 v[62:65], v[182:185], v[198:201], v[62:65]
	v_mfma_f32_16x16x32_bf16 v[54:57], v[186:189], v[194:197], v[54:57]
	v_mfma_f32_16x16x32_bf16 v[54:57], v[190:193], v[198:201], v[54:57]
	v_mfma_f32_16x16x32_bf16 v[46:49], v[160:163], v[202:205], v[46:49]
	v_mfma_f32_16x16x32_bf16 v[46:49], v[182:185], v[206:209], v[46:49]
	v_mfma_f32_16x16x32_bf16 v[38:41], v[186:189], v[202:205], v[38:41]
	v_mfma_f32_16x16x32_bf16 v[38:41], v[190:193], v[206:209], v[38:41]
	v_mfma_f32_16x16x32_bf16 v[30:33], v[160:163], v[210:213], v[30:33]
	v_mfma_f32_16x16x32_bf16 v[30:33], v[182:185], v[214:217], v[30:33]
	v_mfma_f32_16x16x32_bf16 v[22:25], v[186:189], v[210:213], v[22:25]
	v_mfma_f32_16x16x32_bf16 v[22:25], v[190:193], v[214:217], v[22:25]
	v_mfma_f32_16x16x32_bf16 v[10:13], v[160:163], v[218:221], v[10:13]
	v_mfma_f32_16x16x32_bf16 v[10:13], v[182:185], v[222:225], v[10:13]
	v_mfma_f32_16x16x32_bf16 v[2:5], v[186:189], v[218:221], v[2:5]
	v_mfma_f32_16x16x32_bf16 v[2:5], v[190:193], v[222:225], v[2:5]
	s_setprio 0
	s_barrier
	s_add_i32 s40, s40, 2
	s_add_u32 s4, s4, 0x100
	s_addc_u32 s5, s5, 0
	s_add_u32 s38, s38, 0x100
	s_addc_u32 s39, s39, 0
	s_cmp_gt_u32 s40, 13
	s_cbranch_scc1 .Lpeel_exit_3

.Lpeel_exit_3:
	s_and_b64 vcc, exec, s[8:9]
	s_cbranch_vccz .LBB0_896
	s_barrier
